# combo (seam+peel+halfn) + peeled first K-iteration skips phase-1/2 vmcnt waits on non-first tiles so epilogue stores drain under MFMA
# baseline (speedup 1.0000x reference)
; #define PG8_STAGE(bufoff, gbase, voff) do { _Pragma("unroll") for (int _i = 0; _i < 2; ++_i) \
;         __builtin_amdgcn_global_load_lds((const unsigned*)((const char*)(gbase) + (voff)[_i]), (LAS unsigned*)(lds + (bufoff) + ldsw + _i * 8192), 16, 0, 0); } while (0)
; #define PG8_LDA(dst, b, h) do { _Pragma("unroll") for (int m = 0; m < 4; ++m) _Pragma("unroll") for (int k = 0; k < 2; ++k) dst[m][k] = *(const LAS bf16x8*)(lds + PG8_SA(b, h) + aoff + m * 2048 + k * 1024); } while (0)
; #define PG8_LDB(dst, b, h) do { _Pragma("unroll") for (int n = 0; n < 2; ++n) _Pragma("unroll") for (int k = 0; k < 2; ++k) dst[n][k] = *(const LAS bf16x8*)(lds + PG8_SB(b, h) + boff + n * 2048 + k * 1024); } while (0)
; #define PG8_MMA(ai, bj, At, Bt) do { __builtin_amdgcn_s_setprio(1); _Pragma("unroll") for (int m = 0; m < 4; ++m) _Pragma("unroll") for (int n = 0; n < 2; ++n) _Pragma("unroll") for (int k = 0; k < 2; ++k) \
;         acc[ai][bj][m][n] = __builtin_amdgcn_mfma_f32_16x16x32_bf16(Bt[n][k], At[m][k], acc[ai][bj][m][n], 0, 0, 0); __builtin_amdgcn_s_setprio(0); } while (0)
; #define PG8_WAIT_V(n) asm volatile("s_waitcnt vmcnt(" #n ")" ::: "memory")
; #define PG8_WAIT_L(n) asm volatile("s_waitcnt lgkmcnt(" #n ")" ::: "memory")
; #define PG8_BAR __builtin_amdgcn_s_barrier()
; #define PG8_SCHED __builtin_amdgcn_sched_barrier(0)
; template <class Epi, class Order = StaticOrder, bool HALFN = false>
; __device__ __forceinline__ void gemm_phase(LAS unsigned char* lds, const Gemm g, const Epi& E) {
;     ...
;             const char* a1 = cA + (size_t)(t + 1) * kstep;
;             const char* a2 = last ? nA : cA + (size_t)(t + 2) * kstep; const char* b2 = last ? nB : cB + (size_t)(t + 2) * kstep;
;             const char* a3 = a2 + kstep; const char* b3 = b2 + kstep;
;             PG8_LDB(B0, 0, 0); if constexpr (!HALFN) PG8_LDB(B1, 0, 1); PG8_SCHED; PG8_LDA(At, 0, 0); PG8_STAGE(PG8_SA(1, 1), a1 + hstepA, voffA);
;             PG8_WAIT_V(8); PG8_WAIT_L(0); PG8_BAR; PG8_MMA(0, 0, At, B0); if constexpr (!HALFN) PG8_MMA(0, 1, At, B1); PG8_BAR; PG8_SCHED;
;             PG8_LDA(At, 0, 1); PG8_STAGE(PG8_SB(0, 0), b2, voffB); PG8_STAGE(PG8_SB(0, 1), b2 + hstepB, voffB); PG8_STAGE(PG8_SA(0, 0), a2, voffA);
;             PG8_WAIT_V(8); PG8_WAIT_L(0); PG8_BAR; PG8_MMA(1, 0, At, B0); if constexpr (!HALFN) PG8_MMA(1, 1, At, B1); PG8_BAR; PG8_SCHED;
.LBB0_193:
	s_mov_b32 s48, s18
	s_ashr_i32 s49, s18, 31
	s_lshl_b64 s[6:7], s[48:49], 20
	s_add_u32 s74, s0, s6
	s_addc_u32 s75, s1, s7
	s_mov_b32 s50, s9
	s_and_b64 s[6:7], s[54:55], exec
	s_cselect_b32 s8, s75, s63
	s_cselect_b32 s9, s74, s62
	s_ashr_i32 s51, s50, 31
	s_lshl_b64 s[6:7], s[50:51], 20
	s_add_u32 s92, s10, s6
	s_addc_u32 s93, s11, s7
	s_and_b64 s[6:7], s[54:55], exec
	s_cselect_b32 s18, s93, s5
	s_cselect_b32 s19, s92, s4
	s_add_u32 s62, s62, 0x80080
	s_addc_u32 s63, s63, 0
	s_add_u32 s20, s4, 0x100
	s_addc_u32 s21, s5, 0
	s_mov_b32 s22, -2
	s_add_u32 s4, s62, 0xfff80080
	s_addc_u32 s5, s63, -1
	s_add_i32 s23, 0, 0x10000
	s_cmp_eq_u32 s22, 28
	s_cselect_b32 s7, s8, s5
	s_cselect_b32 s6, s9, s4
	v_add_u32_e32 v142, s23, v145
	s_cselect_b32 s5, s18, s21
	s_cselect_b32 s4, s19, s20
	s_add_i32 s26, 0, 0x14000
	ds_read_b128 v[148:151], v142
	ds_read_b128 v[152:155], v142 offset:1024
	ds_read_b128 v[156:159], v142 offset:2048
	ds_read_b128 v[168:171], v142 offset:3072
	v_add_u32_e32 v142, s26, v145
	ds_read_b128 v[172:175], v142
	ds_read_b128 v[176:179], v142 offset:1024
	ds_read_b128 v[180:183], v142 offset:2048
	ds_read_b128 v[184:187], v142 offset:3072
	v_lshl_add_u64 v[160:161], s[62:63], 0, v[138:139]
	s_add_i32 m0, s53, 0xc000
	ds_read_b128 v[208:211], v147
	ds_read_b128 v[212:215], v147 offset:1024
	ds_read_b128 v[216:219], v147 offset:2048
	ds_read_b128 v[220:223], v147 offset:3072
	ds_read_b128 v[224:227], v147 offset:4096
	ds_read_b128 v[228:231], v147 offset:5120
	ds_read_b128 v[232:235], v147 offset:6144
	ds_read_b128 v[236:239], v147 offset:7168
	global_load_lds_dwordx4 v[160:161], off
	v_lshl_add_u64 v[160:161], s[62:63], 0, v[140:141]
	s_add_i32 m0, s53, 0xe000
	s_nop 0
	global_load_lds_dwordx4 v[160:161], off
	s_cmp_eq_u32 s17, 1
	s_cbranch_scc0 .Lrlx1
	s_waitcnt vmcnt(8)
.Lrlx1:
	s_waitcnt lgkmcnt(0)
	s_barrier
	s_setprio 1
	s_waitcnt lgkmcnt(0)
	v_mfma_f32_16x16x32_bf16 v[126:129], v[148:151], v[208:211], 0
	v_mfma_f32_16x16x32_bf16 v[122:125], v[156:159], v[208:211], 0
	v_mfma_f32_16x16x32_bf16 v[114:117], v[148:151], v[216:219], 0
	v_mfma_f32_16x16x32_bf16 v[106:109], v[156:159], v[216:219], 0
	v_mfma_f32_16x16x32_bf16 v[102:105], v[148:151], v[224:227], 0
	v_mfma_f32_16x16x32_bf16 v[94:97], v[156:159], v[224:227], 0
	v_mfma_f32_16x16x32_bf16 v[86:89], v[148:151], v[232:235], 0
	v_mfma_f32_16x16x32_bf16 v[78:81], v[156:159], v[232:235], 0
	v_mfma_f32_16x16x32_bf16 v[126:129], v[152:155], v[212:215], v[126:129]
	v_mfma_f32_16x16x32_bf16 v[122:125], v[168:171], v[212:215], v[122:125]
	v_mfma_f32_16x16x32_bf16 v[114:117], v[152:155], v[220:223], v[114:117]
	v_mfma_f32_16x16x32_bf16 v[106:109], v[168:171], v[220:223], v[106:109]
	v_mfma_f32_16x16x32_bf16 v[102:105], v[152:155], v[228:231], v[102:105]
	v_mfma_f32_16x16x32_bf16 v[94:97], v[168:171], v[228:231], v[94:97]
	v_mfma_f32_16x16x32_bf16 v[86:89], v[152:155], v[236:239], v[86:89]
	v_mfma_f32_16x16x32_bf16 v[78:81], v[168:171], v[236:239], v[78:81]
	s_setprio 0
	s_setprio 1
	v_mfma_f32_16x16x32_bf16 v[118:121], v[172:175], v[208:211], 0
	v_mfma_f32_16x16x32_bf16 v[110:113], v[180:183], v[208:211], 0
	v_mfma_f32_16x16x32_bf16 v[98:101], v[172:175], v[216:219], 0
	v_mfma_f32_16x16x32_bf16 v[90:93], v[180:183], v[216:219], 0
	v_mfma_f32_16x16x32_bf16 v[82:85], v[172:175], v[224:227], 0
	v_mfma_f32_16x16x32_bf16 v[74:77], v[180:183], v[224:227], 0
	v_mfma_f32_16x16x32_bf16 v[70:73], v[172:175], v[232:235], 0
	v_mfma_f32_16x16x32_bf16 v[66:69], v[180:183], v[232:235], 0
	v_mfma_f32_16x16x32_bf16 v[118:121], v[176:179], v[212:215], v[118:121]
	v_mfma_f32_16x16x32_bf16 v[110:113], v[184:187], v[212:215], v[110:113]
	v_mfma_f32_16x16x32_bf16 v[98:101], v[176:179], v[220:223], v[98:101]
	v_mfma_f32_16x16x32_bf16 v[90:93], v[184:187], v[220:223], v[90:93]
	v_mfma_f32_16x16x32_bf16 v[82:85], v[176:179], v[228:231], v[82:85]
	v_mfma_f32_16x16x32_bf16 v[74:77], v[184:187], v[228:231], v[74:77]
	v_mfma_f32_16x16x32_bf16 v[70:73], v[176:179], v[236:239], v[70:73]
	v_mfma_f32_16x16x32_bf16 v[66:69], v[184:187], v[236:239], v[66:69]
	s_setprio 0
	s_barrier
	s_add_i32 s23, s23, s56
	v_lshl_add_u64 v[160:161], s[4:5], 0, v[132:133]
	s_mov_b32 m0, s23
	ds_read_b128 v[208:211], v147 offset:16384
	ds_read_b128 v[212:215], v147 offset:17408
	ds_read_b128 v[216:219], v147 offset:18432
	ds_read_b128 v[220:223], v147 offset:19456
	ds_read_b128 v[224:227], v147 offset:20480
	ds_read_b128 v[228:231], v147 offset:21504
	ds_read_b128 v[232:235], v147 offset:22528
	ds_read_b128 v[236:239], v147 offset:23552
	global_load_lds_dwordx4 v[160:161], off
	s_add_i32 m0, s23, 0x2000
	s_add_u32 s24, s4, 0x80000
	v_lshl_add_u64 v[240:241], s[4:5], 0, v[136:137]
	s_addc_u32 s25, s5, 0
	s_add_i32 s23, s26, s56
	global_load_lds_dwordx4 v[240:241], off
	v_lshl_add_u64 v[242:243], s[24:25], 0, v[132:133]
	s_mov_b32 m0, s23
	v_lshl_add_u64 v[244:245], s[6:7], 0, v[134:135]
	global_load_lds_dwordx4 v[242:243], off
	v_lshl_add_u64 v[242:243], s[24:25], 0, v[136:137]
	s_add_i32 m0, s23, 0x2000
	s_nop 0
	global_load_lds_dwordx4 v[242:243], off
	v_lshl_add_u64 v[242:243], s[6:7], 0, v[130:131]
	s_mov_b32 m0, s53
	s_nop 0
	global_load_lds_dwordx4 v[242:243], off
	s_mov_b32 m0, s80
	s_nop 0
	global_load_lds_dwordx4 v[244:245], off
	s_cmp_eq_u32 s17, 1
	s_cbranch_scc0 .Lrlx0
	s_waitcnt vmcnt(8)
; #define PG8_STAGE(bufoff, gbase, voff) do { _Pragma("unroll") for (int _i = 0; _i < 2; ++_i) \
;         __builtin_amdgcn_global_load_lds((const unsigned*)((const char*)(gbase) + (voff)[_i]), (LAS unsigned*)(lds + (bufoff) + ldsw + _i * 8192), 16, 0, 0); } while (0)
; #define PG8_LDA(dst, b, h) do { _Pragma("unroll") for (int m = 0; m < 4; ++m) _Pragma("unroll") for (int k = 0; k < 2; ++k) dst[m][k] = *(const LAS bf16x8*)(lds + PG8_SA(b, h) + aoff + m * 2048 + k * 1024); } while (0)
; #define PG8_LDB(dst, b, h) do { _Pragma("unroll") for (int n = 0; n < 2; ++n) _Pragma("unroll") for (int k = 0; k < 2; ++k) dst[n][k] = *(const LAS bf16x8*)(lds + PG8_SB(b, h) + boff + n * 2048 + k * 1024); } while (0)
; #define PG8_MMA(ai, bj, At, Bt) do { __builtin_amdgcn_s_setprio(1); _Pragma("unroll") for (int m = 0; m < 4; ++m) _Pragma("unroll") for (int n = 0; n < 2; ++n) _Pragma("unroll") for (int k = 0; k < 2; ++k) \
;         acc[ai][bj][m][n] = __builtin_amdgcn_mfma_f32_16x16x32_bf16(Bt[n][k], At[m][k], acc[ai][bj][m][n], 0, 0, 0); __builtin_amdgcn_s_setprio(0); } while (0)
; #define PG8_WAIT_V(n) asm volatile("s_waitcnt vmcnt(" #n ")" ::: "memory")
; #define PG8_WAIT_L(n) asm volatile("s_waitcnt lgkmcnt(" #n ")" ::: "memory")
; #define PG8_BAR __builtin_amdgcn_s_barrier()
; #define PG8_SCHED __builtin_amdgcn_sched_barrier(0)
; template <class Epi, class Order = StaticOrder, bool HALFN = false>
; __device__ __forceinline__ void gemm_phase(LAS unsigned char* lds, const Gemm g, const Epi& E) {
;     ...
;             PG8_WAIT_V(8); PG8_WAIT_L(0); PG8_BAR; PG8_MMA(1, 0, At, B0); if constexpr (!HALFN) PG8_MMA(1, 1, At, B1); PG8_BAR; PG8_SCHED;
;             PG8_LDB(B0, 1, 0); if constexpr (!HALFN) PG8_LDB(B1, 1, 1); PG8_SCHED; PG8_LDA(At, 1, 0); PG8_STAGE(PG8_SA(0, 1), a2 + hstepA, voffA);
;             PG8_WAIT_V(8); PG8_WAIT_L(0); PG8_BAR; PG8_MMA(0, 0, At, B0); if constexpr (!HALFN) PG8_MMA(0, 1, At, B1); PG8_BAR; PG8_SCHED;
.Lrlx0:
	s_waitcnt lgkmcnt(0)
	s_barrier
	s_setprio 1
	s_waitcnt lgkmcnt(0)
	v_mfma_f32_16x16x32_bf16 v[62:65], v[148:151], v[208:211], 0
	v_mfma_f32_16x16x32_bf16 v[58:61], v[156:159], v[208:211], 0
	v_mfma_f32_16x16x32_bf16 v[54:57], v[148:151], v[216:219], 0
	v_mfma_f32_16x16x32_bf16 v[46:49], v[156:159], v[216:219], 0
	v_mfma_f32_16x16x32_bf16 v[38:41], v[148:151], v[224:227], 0
	v_mfma_f32_16x16x32_bf16 v[30:33], v[156:159], v[224:227], 0
	v_mfma_f32_16x16x32_bf16 v[22:25], v[148:151], v[232:235], 0
	v_mfma_f32_16x16x32_bf16 v[14:17], v[156:159], v[232:235], 0
	v_mfma_f32_16x16x32_bf16 v[62:65], v[152:155], v[212:215], v[62:65]
	v_mfma_f32_16x16x32_bf16 v[58:61], v[168:171], v[212:215], v[58:61]
	v_mfma_f32_16x16x32_bf16 v[54:57], v[152:155], v[220:223], v[54:57]
	v_mfma_f32_16x16x32_bf16 v[46:49], v[168:171], v[220:223], v[46:49]
	v_mfma_f32_16x16x32_bf16 v[38:41], v[152:155], v[228:231], v[38:41]
	v_mfma_f32_16x16x32_bf16 v[30:33], v[168:171], v[228:231], v[30:33]
	v_mfma_f32_16x16x32_bf16 v[22:25], v[152:155], v[236:239], v[22:25]
	v_mfma_f32_16x16x32_bf16 v[14:17], v[168:171], v[236:239], v[14:17]
	s_setprio 0
	s_setprio 1
	v_mfma_f32_16x16x32_bf16 v[50:53], v[172:175], v[208:211], 0
	v_mfma_f32_16x16x32_bf16 v[42:45], v[180:183], v[208:211], 0
	v_mfma_f32_16x16x32_bf16 v[34:37], v[172:175], v[216:219], 0
	v_mfma_f32_16x16x32_bf16 v[26:29], v[180:183], v[216:219], 0
	v_mfma_f32_16x16x32_bf16 v[18:21], v[172:175], v[224:227], 0
	v_mfma_f32_16x16x32_bf16 v[10:13], v[180:183], v[224:227], 0
	v_mfma_f32_16x16x32_bf16 v[6:9], v[172:175], v[232:235], 0
	v_mfma_f32_16x16x32_bf16 v[2:5], v[180:183], v[232:235], 0
	v_mfma_f32_16x16x32_bf16 v[50:53], v[176:179], v[212:215], v[50:53]
	v_mfma_f32_16x16x32_bf16 v[42:45], v[184:187], v[212:215], v[42:45]
	v_mfma_f32_16x16x32_bf16 v[34:37], v[176:179], v[220:223], v[34:37]
	v_mfma_f32_16x16x32_bf16 v[26:29], v[184:187], v[220:223], v[26:29]
	v_mfma_f32_16x16x32_bf16 v[18:21], v[176:179], v[228:231], v[18:21]
	v_mfma_f32_16x16x32_bf16 v[10:13], v[184:187], v[228:231], v[10:13]
	v_mfma_f32_16x16x32_bf16 v[6:9], v[176:179], v[236:239], v[6:9]
	v_mfma_f32_16x16x32_bf16 v[2:5], v[184:187], v[236:239], v[2:5]
	s_setprio 0
	s_barrier
	s_add_i32 s23, 0, 0x18000
	v_add_u32_e32 v142, s23, v145
	s_add_i32 s24, 0, 0x1c000
	ds_read_b128 v[148:151], v142
	ds_read_b128 v[152:155], v142 offset:1024
	ds_read_b128 v[156:159], v142 offset:2048
	ds_read_b128 v[168:171], v142 offset:3072
	v_add_u32_e32 v142, s24, v145
	ds_read_b128 v[172:175], v142
	ds_read_b128 v[176:179], v142 offset:1024
	ds_read_b128 v[180:183], v142 offset:2048
	ds_read_b128 v[184:187], v142 offset:3072
	s_add_u32 s6, s6, 0x80000
	s_addc_u32 s7, s7, 0
	s_mov_b32 m0, s81
	v_lshl_add_u64 v[246:247], s[6:7], 0, v[130:131]
	ds_read_b128 v[208:211], v147 offset:32768
	ds_read_b128 v[212:215], v147 offset:33792
	ds_read_b128 v[216:219], v147 offset:34816
	ds_read_b128 v[220:223], v147 offset:35840
	ds_read_b128 v[224:227], v147 offset:36864
	ds_read_b128 v[228:231], v147 offset:37888
	ds_read_b128 v[232:235], v147 offset:38912
	ds_read_b128 v[236:239], v147 offset:39936
	global_load_lds_dwordx4 v[246:247], off
	v_lshl_add_u64 v[246:247], s[6:7], 0, v[134:135]
	s_mov_b32 m0, s82
	s_nop 0
	global_load_lds_dwordx4 v[246:247], off
	s_waitcnt vmcnt(8)
	s_waitcnt lgkmcnt(0)
	s_barrier
	s_setprio 1
	s_waitcnt lgkmcnt(0)
	v_mfma_f32_16x16x32_bf16 v[126:129], v[148:151], v[208:211], v[126:129]
	v_mfma_f32_16x16x32_bf16 v[122:125], v[156:159], v[208:211], v[122:125]
	v_mfma_f32_16x16x32_bf16 v[114:117], v[148:151], v[216:219], v[114:117]
	v_mfma_f32_16x16x32_bf16 v[106:109], v[156:159], v[216:219], v[106:109]
	v_mfma_f32_16x16x32_bf16 v[102:105], v[148:151], v[224:227], v[102:105]
	v_mfma_f32_16x16x32_bf16 v[94:97], v[156:159], v[224:227], v[94:97]
	v_mfma_f32_16x16x32_bf16 v[86:89], v[148:151], v[232:235], v[86:89]
	v_mfma_f32_16x16x32_bf16 v[78:81], v[156:159], v[232:235], v[78:81]
	v_mfma_f32_16x16x32_bf16 v[126:129], v[152:155], v[212:215], v[126:129]
	v_mfma_f32_16x16x32_bf16 v[122:125], v[168:171], v[212:215], v[122:125]
	v_mfma_f32_16x16x32_bf16 v[114:117], v[152:155], v[220:223], v[114:117]
	v_mfma_f32_16x16x32_bf16 v[106:109], v[168:171], v[220:223], v[106:109]
	v_mfma_f32_16x16x32_bf16 v[102:105], v[152:155], v[228:231], v[102:105]
	v_mfma_f32_16x16x32_bf16 v[94:97], v[168:171], v[228:231], v[94:97]
	v_mfma_f32_16x16x32_bf16 v[86:89], v[152:155], v[236:239], v[86:89]
	v_mfma_f32_16x16x32_bf16 v[78:81], v[168:171], v[236:239], v[78:81]
	s_setprio 0
	s_setprio 1
	v_mfma_f32_16x16x32_bf16 v[118:121], v[172:175], v[208:211], v[118:121]
	v_mfma_f32_16x16x32_bf16 v[110:113], v[180:183], v[208:211], v[110:113]
	v_mfma_f32_16x16x32_bf16 v[98:101], v[172:175], v[216:219], v[98:101]
	v_mfma_f32_16x16x32_bf16 v[90:93], v[180:183], v[216:219], v[90:93]
	v_mfma_f32_16x16x32_bf16 v[82:85], v[172:175], v[224:227], v[82:85]
	v_mfma_f32_16x16x32_bf16 v[74:77], v[180:183], v[224:227], v[74:77]
	v_mfma_f32_16x16x32_bf16 v[70:73], v[172:175], v[232:235], v[70:73]
	v_mfma_f32_16x16x32_bf16 v[66:69], v[180:183], v[232:235], v[66:69]
	v_mfma_f32_16x16x32_bf16 v[118:121], v[176:179], v[212:215], v[118:121]
	v_mfma_f32_16x16x32_bf16 v[110:113], v[184:187], v[212:215], v[110:113]
	v_mfma_f32_16x16x32_bf16 v[98:101], v[176:179], v[220:223], v[98:101]
	v_mfma_f32_16x16x32_bf16 v[90:93], v[184:187], v[220:223], v[90:93]
	v_mfma_f32_16x16x32_bf16 v[82:85], v[176:179], v[228:231], v[82:85]
	v_mfma_f32_16x16x32_bf16 v[74:77], v[184:187], v[228:231], v[74:77]
	v_mfma_f32_16x16x32_bf16 v[70:73], v[176:179], v[236:239], v[70:73]
	v_mfma_f32_16x16x32_bf16 v[66:69], v[184:187], v[236:239], v[66:69]
	s_setprio 0
	s_barrier
; #define PG8_STAGE(bufoff, gbase, voff) do { _Pragma("unroll") for (int _i = 0; _i < 2; ++_i) \
;         __builtin_amdgcn_global_load_lds((const unsigned*)((const char*)(gbase) + (voff)[_i]), (LAS unsigned*)(lds + (bufoff) + ldsw + _i * 8192), 16, 0, 0); } while (0)
; #define PG8_LDA(dst, b, h) do { _Pragma("unroll") for (int m = 0; m < 4; ++m) _Pragma("unroll") for (int k = 0; k < 2; ++k) dst[m][k] = *(const LAS bf16x8*)(lds + PG8_SA(b, h) + aoff + m * 2048 + k * 1024); } while (0)
; #define PG8_MMA(ai, bj, At, Bt) do { __builtin_amdgcn_s_setprio(1); _Pragma("unroll") for (int m = 0; m < 4; ++m) _Pragma("unroll") for (int n = 0; n < 2; ++n) _Pragma("unroll") for (int k = 0; k < 2; ++k) \
;         acc[ai][bj][m][n] = __builtin_amdgcn_mfma_f32_16x16x32_bf16(Bt[n][k], At[m][k], acc[ai][bj][m][n], 0, 0, 0); __builtin_amdgcn_s_setprio(0); } while (0)
; #define PG8_WAIT_V(n) asm volatile("s_waitcnt vmcnt(" #n ")" ::: "memory")
; #define PG8_WAIT_L(n) asm volatile("s_waitcnt lgkmcnt(" #n ")" ::: "memory")
; #define PG8_BAR __builtin_amdgcn_s_barrier()
; #define PG8_SCHED __builtin_amdgcn_sched_barrier(0)
; template <class Epi, class Order = StaticOrder, bool HALFN = false>
; __device__ __forceinline__ void gemm_phase(LAS unsigned char* lds, const Gemm g, const Epi& E) {
;     ...
;             PG8_LDA(At, 1, 1); PG8_STAGE(PG8_SB(1, 0), b3, voffB); PG8_STAGE(PG8_SB(1, 1), b3 + hstepB, voffB); PG8_STAGE(PG8_SA(1, 0), a3, voffA);
;             PG8_WAIT_V(8); PG8_WAIT_L(0); PG8_BAR; PG8_MMA(1, 0, At, B0); if constexpr (!HALFN) PG8_MMA(1, 1, At, B1); PG8_BAR; PG8_SCHED;
;         }
	s_add_i32 s6, s23, s56
	v_lshl_add_u64 v[160:161], v[160:161], 0, s[60:61]
	s_mov_b32 m0, s6
	ds_read_b128 v[208:211], v147 offset:49152
	ds_read_b128 v[212:215], v147 offset:50176
	ds_read_b128 v[216:219], v147 offset:51200
	ds_read_b128 v[220:223], v147 offset:52224
	ds_read_b128 v[224:227], v147 offset:53248
	ds_read_b128 v[228:231], v147 offset:54272
	ds_read_b128 v[232:235], v147 offset:55296
	ds_read_b128 v[236:239], v147 offset:56320
	global_load_lds_dwordx4 v[160:161], off
	s_add_i32 m0, s6, 0x2000
	s_add_u32 s4, s4, 0x80080
	v_lshl_add_u64 v[160:161], v[240:241], 0, s[60:61]
	s_addc_u32 s5, s5, 0
	s_add_i32 s6, s24, s56
	global_load_lds_dwordx4 v[160:161], off
	v_lshl_add_u64 v[160:161], s[4:5], 0, v[132:133]
	s_mov_b32 m0, s6
	s_nop 0
	global_load_lds_dwordx4 v[160:161], off
	v_lshl_add_u64 v[160:161], s[4:5], 0, v[136:137]
	s_add_i32 m0, s6, 0x2000
	s_nop 0
	global_load_lds_dwordx4 v[160:161], off
	v_lshl_add_u64 v[160:161], v[242:243], 0, s[60:61]
	s_mov_b32 m0, s95
	s_nop 0
	global_load_lds_dwordx4 v[160:161], off
	v_lshl_add_u64 v[160:161], v[244:245], 0, s[60:61]
	s_mov_b32 m0, s15
	s_nop 0
	global_load_lds_dwordx4 v[160:161], off
	s_waitcnt vmcnt(8)
	s_waitcnt lgkmcnt(0)
	s_barrier
	s_setprio 1
	s_waitcnt lgkmcnt(0)
	v_mfma_f32_16x16x32_bf16 v[62:65], v[148:151], v[208:211], v[62:65]
	v_mfma_f32_16x16x32_bf16 v[58:61], v[156:159], v[208:211], v[58:61]
	v_mfma_f32_16x16x32_bf16 v[54:57], v[148:151], v[216:219], v[54:57]
	v_mfma_f32_16x16x32_bf16 v[46:49], v[156:159], v[216:219], v[46:49]
	v_mfma_f32_16x16x32_bf16 v[38:41], v[148:151], v[224:227], v[38:41]
	v_mfma_f32_16x16x32_bf16 v[30:33], v[156:159], v[224:227], v[30:33]
	v_mfma_f32_16x16x32_bf16 v[22:25], v[148:151], v[232:235], v[22:25]
	v_mfma_f32_16x16x32_bf16 v[14:17], v[156:159], v[232:235], v[14:17]
	v_mfma_f32_16x16x32_bf16 v[62:65], v[152:155], v[212:215], v[62:65]
	v_mfma_f32_16x16x32_bf16 v[58:61], v[168:171], v[212:215], v[58:61]
	v_mfma_f32_16x16x32_bf16 v[54:57], v[152:155], v[220:223], v[54:57]
	v_mfma_f32_16x16x32_bf16 v[46:49], v[168:171], v[220:223], v[46:49]
	v_mfma_f32_16x16x32_bf16 v[38:41], v[152:155], v[228:231], v[38:41]
	v_mfma_f32_16x16x32_bf16 v[30:33], v[168:171], v[228:231], v[30:33]
	v_mfma_f32_16x16x32_bf16 v[22:25], v[152:155], v[236:239], v[22:25]
	v_mfma_f32_16x16x32_bf16 v[14:17], v[168:171], v[236:239], v[14:17]
	s_setprio 0
	s_setprio 1
	v_mfma_f32_16x16x32_bf16 v[50:53], v[172:175], v[208:211], v[50:53]
	v_mfma_f32_16x16x32_bf16 v[42:45], v[180:183], v[208:211], v[42:45]
	v_mfma_f32_16x16x32_bf16 v[34:37], v[172:175], v[216:219], v[34:37]
	v_mfma_f32_16x16x32_bf16 v[26:29], v[180:183], v[216:219], v[26:29]
	v_mfma_f32_16x16x32_bf16 v[18:21], v[172:175], v[224:227], v[18:21]
	v_mfma_f32_16x16x32_bf16 v[10:13], v[180:183], v[224:227], v[10:13]
	v_mfma_f32_16x16x32_bf16 v[6:9], v[172:175], v[232:235], v[6:9]
	v_mfma_f32_16x16x32_bf16 v[2:5], v[180:183], v[232:235], v[2:5]
	v_mfma_f32_16x16x32_bf16 v[50:53], v[176:179], v[212:215], v[50:53]
	v_mfma_f32_16x16x32_bf16 v[42:45], v[184:187], v[212:215], v[42:45]
	v_mfma_f32_16x16x32_bf16 v[34:37], v[176:179], v[220:223], v[34:37]
	v_mfma_f32_16x16x32_bf16 v[26:29], v[184:187], v[220:223], v[26:29]
	v_mfma_f32_16x16x32_bf16 v[18:21], v[176:179], v[228:231], v[18:21]
	v_mfma_f32_16x16x32_bf16 v[10:13], v[184:187], v[228:231], v[10:13]
	v_mfma_f32_16x16x32_bf16 v[6:9], v[176:179], v[236:239], v[6:9]
	v_mfma_f32_16x16x32_bf16 v[2:5], v[184:187], v[236:239], v[2:5]
	s_setprio 0
	s_barrier
	s_add_i32 s22, s22, 2
	s_add_u32 s62, s62, 0x100
	s_addc_u32 s63, s63, 0
	s_add_u32 s20, s20, 0x100
	s_addc_u32 s21, s21, 0
	s_cmp_gt_u32 s22, 29
